# phase dispatch: GEMM phases enter the kind loop at their first active kind and leave after the last; phases with only hand-written row/scan units skip the unused address setup
# speedup vs baseline: 1.0198x; 1.0039x over previous
.LBB0_165:
	s_add_i32 s0, s36, 9
	s_add_u32 s71, s4, 0x3800000
	s_addc_u32 s72, s5, 0
	s_cmp_lt_u32 s0, 21
	v_writelane_b32 v245, s36, 37
	s_cselect_b64 s[0:1], -1, 0
	v_writelane_b32 v245, s0, 38
	s_mov_b32 s24, 0
	s_nop 0
	v_writelane_b32 v245, s1, 39
	s_and_b64 s[0:1], s[0:1], exec
	s_cselect_b32 s7, 0, 0x400
	s_cselect_b32 s100, 1, 0
	s_mov_b32 s101, 0x900
	s_bitcmp1_b32 s101, s36
	s_cselect_b32 s7, 0x400, s7
	s_cmp_eq_u32 s100, 1
	v_writelane_b32 v245, s7, 40
	s_and_b32 s0, s94, 0x15001
	s_cmp_eq_u32 s0, s94
	s_cbranch_scc0 .Lfull_setup
	v_writelane_b32 v247, s70, 28
	v_writelane_b32 v244, s71, 30
	v_writelane_b32 v244, s72, 31
	s_xor_b32 s46, s7, 0x4400
	s_lshr_b32 s47, s7, 8
	s_branch .Lgemm_skip_state
.Lfull_setup:
	s_cmp_eq_u32 s100, 1
	s_cselect_b32 s0, s16, s71
	v_writelane_b32 v245, s0, 41
	s_cselect_b32 s0, s17, s72
	s_xor_b32 s46, s7, 0x4400
	s_mul_i32 s1, s70, 0x1600000
	v_writelane_b32 v245, s0, 42
	s_mul_hi_i32 s0, s70, 0x1600000
	s_add_u32 s1, s4, s1
	s_addc_u32 s0, s5, s0
	s_add_u32 s8, s1, 0xc00000
	s_addc_u32 s9, s0, 0
	v_writelane_b32 v245, s8, 43
	s_nop 1
	v_writelane_b32 v245, s9, 44
	s_add_u32 s8, s4, 0x3c00000
	s_addc_u32 s9, s5, 0
	s_lshl_b32 s6, s7, 11
	s_add_u32 s10, s8, s6
	v_writelane_b32 v245, s8, 45
	s_addc_u32 s11, s9, 0
	s_nop 0
	v_writelane_b32 v245, s9, 46
	v_writelane_b32 v245, s10, 47
	s_add_u32 s8, s1, 0x1000000
	s_addc_u32 s9, s0, 0
	v_writelane_b32 v245, s11, 48
	v_writelane_b32 v245, s8, 49
	s_nop 1
	v_writelane_b32 v245, s9, 50
	s_add_u32 s8, s1, 0x1200000
	s_addc_u32 s9, s0, 0
	v_writelane_b32 v245, s8, 51
	s_nop 1
	v_writelane_b32 v245, s9, 52
	s_add_u32 s8, s4, 0xc500000
	s_addc_u32 s9, s5, 0
	s_lshl_b32 s6, s7, 9
	s_add_u32 s10, s8, s6
	v_writelane_b32 v245, s8, 53
	s_addc_u32 s11, s9, 0
	s_nop 0
	v_writelane_b32 v245, s9, 54
	v_writelane_b32 v245, s10, 55
	s_add_u32 s8, s1, 0xfc0000
	s_addc_u32 s9, s0, 0
	v_writelane_b32 v245, s11, 56
	v_writelane_b32 v245, s8, 57
	s_nop 1
	v_writelane_b32 v245, s9, 58
	s_add_u32 s8, s4, 0xbc00000
	s_addc_u32 s9, s5, 0
	v_writelane_b32 v245, s8, 59
	s_add_u32 s8, s8, s6
	v_writelane_b32 v245, s9, 60
	s_addc_u32 s9, s9, 0
	v_writelane_b32 v245, s8, 61
	s_nop 1
	v_writelane_b32 v245, s9, 62
	s_add_u32 s8, s1, 0xfa0000
	s_addc_u32 s9, s0, 0
	v_writelane_b32 v245, s8, 63
	s_nop 1
	v_writelane_b32 v244, s9, 0
	s_add_u32 s8, s4, 0xa300000
	s_addc_u32 s9, s5, 0
	s_add_u32 s10, s8, s6
	v_writelane_b32 v244, s8, 1
	s_addc_u32 s11, s9, 0
	s_nop 0
	v_writelane_b32 v244, s9, 2
	v_writelane_b32 v244, s10, 3
	s_add_u32 s8, s1, 0xf80000
	s_addc_u32 s9, s0, 0
	v_writelane_b32 v244, s11, 4
	v_writelane_b32 v244, s8, 5
	s_nop 1
	v_writelane_b32 v244, s9, 6
	s_add_u32 s8, s1, 0xe80000
	s_addc_u32 s9, s0, 0
	v_writelane_b32 v244, s8, 7
	s_nop 1
	v_writelane_b32 v244, s9, 8
	s_add_u32 s8, s4, 0x5e00000
	s_addc_u32 s9, s5, 0
	s_lshl_b32 s6, s7, 13
	s_add_u32 s10, s8, s6
	v_writelane_b32 v247, s8, 26
	s_addc_u32 s11, s9, 0
	v_writelane_b32 v244, s10, 9
	v_writelane_b32 v247, s9, 27
	s_add_u32 s8, s1, 0x1a00000
	s_addc_u32 s9, s0, 0
	s_lshl_b32 s0, s70, 10
	v_writelane_b32 v244, s11, 10
	s_ashr_i32 s1, s0, 31
	v_writelane_b32 v244, s8, 11
	s_lshr_b32 s47, s7, 8
	s_lshl_b64 s[0:1], s[0:1], 2
	v_writelane_b32 v244, s9, 12
	s_add_u32 s6, s4, s0
	v_writelane_b32 v244, s6, 13
	v_writelane_b32 v244, s0, 14
	s_nop 1
	v_writelane_b32 v244, s1, 15
	s_addc_u32 s0, s5, s1
	v_writelane_b32 v244, s0, 16
	s_add_u32 s0, s4, 0xce00000
	s_addc_u32 s1, s5, 0
	v_writelane_b32 v244, s0, 17
	s_nop 1
	v_writelane_b32 v244, s1, 18
	s_lshl_b32 s0, s70, 9
	s_ashr_i32 s1, s0, 31
	s_lshl_b64 s[0:1], s[0:1], 2
	s_add_u32 s0, s4, s0
	s_addc_u32 s1, s5, s1
	s_add_u32 s0, s0, 0x220320
	s_addc_u32 s1, s1, 0
	v_writelane_b32 v244, s0, 19
	s_lshl_b32 s6, s70, 8
	s_ashr_i32 s7, s6, 31
	v_writelane_b32 v244, s1, 20
	s_mov_b32 s0, s6
	v_writelane_b32 v244, s0, 21
	s_lshl_b64 s[6:7], s[6:7], 2
	s_nop 0
	v_writelane_b32 v244, s1, 22
	s_add_u32 s0, s4, s6
	v_writelane_b32 v244, s6, 23
	s_addc_u32 s1, s5, s7
	s_add_u32 s8, s0, 0x113800
	s_addc_u32 s9, s1, 0
	s_add_u32 s28, s4, 0xdf00000
	s_addc_u32 s29, s5, 0
	s_add_u32 s84, s0, 0x113000
	s_addc_u32 s85, s1, 0
	v_writelane_b32 v244, s7, 24
	s_add_u32 s0, s4, 0x9a00000
	v_writelane_b32 v244, s0, 25
	s_addc_u32 s0, s5, 0
	v_writelane_b32 v244, s0, 26
	s_add_u32 s0, s4, 0xa200000
	v_writelane_b32 v247, s0, 25
	s_addc_u32 s0, s5, 0
	v_writelane_b32 v244, s0, 27
	s_lshl_b32 s0, s70, 12
	s_ashr_i32 s1, s0, 31
	s_lshl_b64 s[0:1], s[0:1], 2
	s_add_u32 s0, s4, s0
	s_addc_u32 s1, s5, s1
	s_add_u32 s0, s0, 0x227320
	s_addc_u32 s1, s1, 0
	v_writelane_b32 v244, s0, 28
	v_writelane_b32 v247, s70, 28
	s_nop 0
	v_writelane_b32 v244, s1, 29
	v_writelane_b32 v244, s71, 30
	v_writelane_b32 v244, s72, 31
	s_and_b32 s0, s94, 0x6a906
	s_cmp_lg_u32 s0, 0
	s_cbranch_scc1 .Lgemm_phase
.Lgemm_skip_state:
	s_mov_b32 s24, 8
	s_mov_b64 s[14:15], 0
	s_mov_b32 s6, 0
	s_mov_b64 s[0:1], -1
	s_mov_b64 vcc, exec
	s_cmp_eq_u32 s24, 8
	s_branch .LBB0_342
.Lgemm_phase:
	s_mov_b32 s24, 0
	s_bitcmp1_b32 s94, 18
	s_cselect_b32 s24, 7, s24
	s_bitcmp1_b32 s94, 15
	s_cselect_b32 s24, 6, s24
	s_bitcmp1_b32 s94, 17
	s_cselect_b32 s24, 5, s24
	s_and_b32 s0, s94, 0x2906
	s_cmp_lg_u32 s0, 0
	s_cselect_b32 s24, 0, s24
	s_branch .LBB0_168

.LBB0_167:
	s_add_i32 s24, s24, 1
	s_cmp_eq_u32 s24, 8
	s_cbranch_scc1 .LBB0_342
	s_cmp_lt_u32 s24, 2
	s_cbranch_scc1 .LBB0_168
	s_and_b32 s6, s94, 0x6a900
	s_cmp_eq_u32 s6, 0
	s_cbranch_scc1 .Lgemm_skip_state
	s_cmp_lt_u32 s24, 6
	s_cbranch_scc1 .LBB0_168
	s_and_b32 s6, s94, 0x48000
	s_cmp_eq_u32 s6, 0
	s_cbranch_scc1 .Lgemm_skip_state
	s_cmp_lt_u32 s24, 7
	s_cbranch_scc1 .LBB0_168
	s_bitcmp1_b32 s94, 18
	s_cbranch_scc0 .Lgemm_skip_state
